# FFN1 last (half-full) round shared by block pairs: each block of a pair computes one 128-row half of the tile (other half's MFMAs skipped)
# speedup vs baseline: 1.0056x; 1.0056x over previous
.LBB0_488:
	s_or_b64 exec, exec, s[4:5]
	s_cmp_lg_u32 s22, 1
	s_mov_b64 s[4:5], -1
	s_waitcnt lgkmcnt(0)
	s_barrier
	s_cbranch_scc0 .LBB0_659
	s_mov_b32 s98, 0
	s_mov_b32 s99, 0
	s_lshr_b32 s0, s22, 1
	v_readlane_b32 s1, v251, 55
	s_add_i32 s0, s0, s1
	s_mov_b64 s[4:5], s[68:69]
	s_mov_b64 s[10:11], s[68:69]
	s_mov_b64 s[12:13], s[68:69]
	s_movk_i32 s22, 0x400
	s_movk_i32 s18, 0x400
	s_movk_i32 s6, 0x400
	s_movk_i32 s7, 0x1600
	s_movk_i32 s1, 0x4000
	s_ashr_i32 s8, s1, 31
	s_lshr_b32 s8, s8, 24
	s_add_i32 s1, s1, s8
	s_ashr_i32 s8, s7, 31
	s_lshr_b32 s8, s8, 24
	s_add_i32 s7, s7, s8
	s_ashr_i32 s1, s1, 8
	s_ashr_i32 s20, s7, 8
	s_mul_i32 s8, s20, s1
	v_mov_b32_e32 v12, v196
	v_readlane_b32 s7, v251, 17
	s_cmp_lt_i32 s7, s8
	v_readfirstlane_b32 s24, v12
	s_cbranch_scc0 .LBB0_518
	s_ashr_i32 s9, s8, 31
	s_lshr_b32 s7, s9, 29
	s_add_i32 s7, s8, s7
	s_ashr_i32 s34, s7, 3
	s_and_b32 s7, s7, -8
	s_sub_i32 s35, s8, s7
	s_add_i32 s36, s34, 1
	v_readlane_b32 s7, v251, 18
	s_cmp_ge_i32 s7, s35
	s_mov_b64 s[16:17], -1
	s_mul_i32 s37, s36, s35
	s_cbranch_scc0 .LBB0_492
	v_readlane_b32 s7, v251, 18
	s_sub_i32 s7, s7, s35
	s_mul_i32 s7, s7, s34
	s_add_i32 s21, s7, s37
	s_mov_b64 s[16:17], 0

.LBB0_498:
	s_andn2_b64 vcc, exec, s[28:29]
	s_mov_b32 s58, s56
	s_mov_b32 s59, s57
	s_mov_b32 s98, s99
	s_mov_b64 s[30:31], s[26:27]
	s_mov_b64 s[28:29], s[6:7]
	s_cbranch_vccz .LBB0_517
.LBB0_499:
	s_add_i32 s55, s55, 1
	s_mul_i32 s4, s55, s91
	s_mul_hi_u32 s5, s55, s82
	s_add_i32 s5, s5, s4
	s_mul_i32 s4, s55, s82
	v_readlane_b32 s6, v251, 17
	s_add_u32 s4, s4, s6
	v_readlane_b32 s6, v251, 16
	s_addc_u32 s5, s5, s6
	s_mov_b32 s99, 0
	s_cmp_lg_u32 s82, 0x100
	s_cbranch_scc1 .Lhn_done
	s_and_b32 s6, s8, 0xff
	s_cmp_lg_u32 s6, 0x80
	s_cbranch_scc1 .Lhn_done
	s_sub_i32 s6, s4, s8
	s_cmp_lt_u32 s6, 0x80
	s_cbranch_scc0 .Lhn_notb
	s_sub_u32 s4, s4, 0x80
	s_mov_b32 s99, 2
	s_branch .Lhn_done
.Lhn_notb:
	s_add_i32 s6, s6, 0x80
	s_cmp_lt_u32 s6, 0x80
	s_cselect_b32 s99, 1, 0
.Lhn_done:
	v_mov_b64_e32 v[0:1], s[8:9]
	v_cmp_ge_i64_e32 vcc, s[4:5], v[0:1]
	v_cmp_lt_i64_e64 s[6:7], s[4:5], v[0:1]
	s_cbranch_vccnz .LBB0_505
	s_ashr_i32 s5, s4, 31
	s_lshr_b32 s5, s5, 29
	s_add_i32 s26, s4, s5
	s_and_b32 s5, s26, -8
	s_sub_i32 s27, s4, s5
	s_cmp_ge_i32 s27, s35
	s_mov_b64 s[4:5], -1
	s_cbranch_scc0 .LBB0_502
	s_sub_i32 s4, s27, s35
	s_mul_i32 s4, s4, s34
	s_add_i32 s56, s4, s37
	s_mov_b64 s[4:5], 0

.LBB0_509:
	v_mov_b32_e32 v125, 0
	s_andn2_b64 vcc, exec, s[22:23]
	v_mov_b32_e32 v124, v125
	v_mov_b32_e32 v123, v125
	v_mov_b32_e32 v122, v125
	v_mov_b32_e32 v121, v125
	v_mov_b32_e32 v120, v125
	v_mov_b32_e32 v119, v125
	v_mov_b32_e32 v118, v125
	v_mov_b32_e32 v113, v125
	v_mov_b32_e32 v112, v125
	v_mov_b32_e32 v111, v125
	v_mov_b32_e32 v110, v125
	v_mov_b32_e32 v105, v125
	v_mov_b32_e32 v104, v125
	v_mov_b32_e32 v103, v125
	v_mov_b32_e32 v102, v125
	v_mov_b32_e32 v97, v125
	v_mov_b32_e32 v96, v125
	v_mov_b32_e32 v95, v125
	v_mov_b32_e32 v94, v125
	v_mov_b32_e32 v87, v125
	v_mov_b32_e32 v86, v125
	v_mov_b32_e32 v85, v125
	v_mov_b32_e32 v84, v125
	v_mov_b32_e32 v79, v125
	v_mov_b32_e32 v78, v125
	v_mov_b32_e32 v77, v125
	v_mov_b32_e32 v76, v125
	v_mov_b32_e32 v71, v125
	v_mov_b32_e32 v70, v125
	v_mov_b32_e32 v69, v125
	v_mov_b32_e32 v68, v125
	v_mov_b32_e32 v129, v125
	v_mov_b32_e32 v128, v125
	v_mov_b32_e32 v127, v125
	v_mov_b32_e32 v126, v125
	v_mov_b32_e32 v117, v125
	v_mov_b32_e32 v116, v125
	v_mov_b32_e32 v115, v125
	v_mov_b32_e32 v114, v125
	v_mov_b32_e32 v109, v125
	v_mov_b32_e32 v108, v125
	v_mov_b32_e32 v107, v125
	v_mov_b32_e32 v106, v125
	v_mov_b32_e32 v101, v125
	v_mov_b32_e32 v100, v125
	v_mov_b32_e32 v99, v125
	v_mov_b32_e32 v98, v125
	v_mov_b32_e32 v91, v125
	v_mov_b32_e32 v90, v125
	v_mov_b32_e32 v89, v125
	v_mov_b32_e32 v88, v125
	v_mov_b32_e32 v83, v125
	v_mov_b32_e32 v82, v125
	v_mov_b32_e32 v81, v125
	v_mov_b32_e32 v80, v125
	v_mov_b32_e32 v75, v125
	v_mov_b32_e32 v74, v125
	v_mov_b32_e32 v73, v125
	v_mov_b32_e32 v72, v125
	v_mov_b32_e32 v67, v125
	v_mov_b32_e32 v66, v125
	v_mov_b32_e32 v65, v125
	v_mov_b32_e32 v64, v125
	s_waitcnt vmcnt(0)
	v_mov_b32_e32 v63, v125
	v_mov_b32_e32 v62, v125
	v_mov_b32_e32 v61, v125
	v_mov_b32_e32 v60, v125
	v_mov_b32_e32 v55, v125
	v_mov_b32_e32 v54, v125
	v_mov_b32_e32 v53, v125
	v_mov_b32_e32 v52, v125
	v_mov_b32_e32 v47, v125
	v_mov_b32_e32 v46, v125
	v_mov_b32_e32 v45, v125
	v_mov_b32_e32 v44, v125
	v_mov_b32_e32 v39, v125
	v_mov_b32_e32 v38, v125
	v_mov_b32_e32 v37, v125
	v_mov_b32_e32 v36, v125
	v_mov_b32_e32 v31, v125
	v_mov_b32_e32 v30, v125
	v_mov_b32_e32 v29, v125
	v_mov_b32_e32 v28, v125
	v_mov_b32_e32 v23, v125
	v_mov_b32_e32 v22, v125
	v_mov_b32_e32 v21, v125
	v_mov_b32_e32 v20, v125
	v_mov_b32_e32 v15, v125
	v_mov_b32_e32 v14, v125
	v_mov_b32_e32 v13, v125
	v_mov_b32_e32 v12, v125
	v_mov_b32_e32 v7, v125
	v_mov_b32_e32 v6, v125
	v_mov_b32_e32 v5, v125
	v_mov_b32_e32 v4, v125
	v_mov_b32_e32 v59, v125
	v_mov_b32_e32 v58, v125
	v_mov_b32_e32 v57, v125
	v_mov_b32_e32 v56, v125
	v_mov_b32_e32 v51, v125
	v_mov_b32_e32 v50, v125
	v_mov_b32_e32 v49, v125
	v_mov_b32_e32 v48, v125
	v_mov_b32_e32 v43, v125
	v_mov_b32_e32 v42, v125
	v_mov_b32_e32 v41, v125
	v_mov_b32_e32 v40, v125
	v_mov_b32_e32 v35, v125
	v_mov_b32_e32 v34, v125
	v_mov_b32_e32 v33, v125
	v_mov_b32_e32 v32, v125
	v_mov_b32_e32 v27, v125
	v_mov_b32_e32 v26, v125
	v_mov_b32_e32 v25, v125
	v_mov_b32_e32 v24, v125
	v_mov_b32_e32 v19, v125
	v_mov_b32_e32 v18, v125
	v_mov_b32_e32 v17, v125
	v_mov_b32_e32 v16, v125
	v_mov_b32_e32 v11, v125
	v_mov_b32_e32 v10, v125
	v_mov_b32_e32 v9, v125
	v_mov_b32_e32 v8, v125
	v_mov_b32_e32 v3, v125
	v_mov_b32_e32 v2, v125
	v_mov_b32_e32 v1, v125
	v_mov_b32_e32 v0, v125
	s_cbranch_vccnz .LBB0_512
	s_add_u32 s28, s28, 0x80
	s_addc_u32 s29, s29, 0
	s_add_u32 s60, s30, 0x100
	v_mov_b32_e32 v0, 0
	s_addc_u32 s61, s31, 0
	s_mov_b32 s30, 0
	v_mov_b32_e32 v1, v0
	v_mov_b32_e32 v2, v0
	v_mov_b32_e32 v3, v0
	v_mov_b32_e32 v8, v0
	v_mov_b32_e32 v9, v0
	v_mov_b32_e32 v10, v0
	v_mov_b32_e32 v11, v0
	v_mov_b32_e32 v16, v0
	v_mov_b32_e32 v17, v0
	v_mov_b32_e32 v18, v0
	v_mov_b32_e32 v19, v0
	v_mov_b32_e32 v24, v0
	v_mov_b32_e32 v25, v0
	v_mov_b32_e32 v26, v0
	v_mov_b32_e32 v27, v0
	v_mov_b32_e32 v32, v0
	v_mov_b32_e32 v33, v0
	v_mov_b32_e32 v34, v0
	v_mov_b32_e32 v35, v0
	v_mov_b32_e32 v40, v0
	v_mov_b32_e32 v41, v0
	v_mov_b32_e32 v42, v0
	v_mov_b32_e32 v43, v0
	v_mov_b32_e32 v48, v0
	v_mov_b32_e32 v49, v0
	v_mov_b32_e32 v50, v0
	v_mov_b32_e32 v51, v0
	v_mov_b32_e32 v56, v0
	v_mov_b32_e32 v57, v0
	v_mov_b32_e32 v58, v0
	v_mov_b32_e32 v59, v0
	v_mov_b32_e32 v4, v0
	v_mov_b32_e32 v5, v0
	v_mov_b32_e32 v6, v0
	v_mov_b32_e32 v7, v0
	v_mov_b32_e32 v12, v0
	v_mov_b32_e32 v13, v0
	v_mov_b32_e32 v14, v0
	v_mov_b32_e32 v15, v0
	v_mov_b32_e32 v20, v0
	v_mov_b32_e32 v21, v0
	v_mov_b32_e32 v22, v0
	v_mov_b32_e32 v23, v0
	v_mov_b32_e32 v28, v0
	v_mov_b32_e32 v29, v0
	v_mov_b32_e32 v30, v0
	v_mov_b32_e32 v31, v0
	v_mov_b32_e32 v36, v0
	v_mov_b32_e32 v37, v0
	v_mov_b32_e32 v38, v0
	v_mov_b32_e32 v39, v0
	v_mov_b32_e32 v44, v0
	v_mov_b32_e32 v45, v0
	v_mov_b32_e32 v46, v0
	v_mov_b32_e32 v47, v0
	v_mov_b32_e32 v52, v0
	v_mov_b32_e32 v53, v0
	v_mov_b32_e32 v54, v0
	v_mov_b32_e32 v55, v0
	v_mov_b32_e32 v60, v0
	v_mov_b32_e32 v61, v0
	v_mov_b32_e32 v62, v0
	v_mov_b32_e32 v63, v0
	v_mov_b32_e32 v64, v0
	v_mov_b32_e32 v65, v0
	v_mov_b32_e32 v66, v0
	v_mov_b32_e32 v67, v0
	v_mov_b32_e32 v72, v0
	v_mov_b32_e32 v73, v0
	v_mov_b32_e32 v74, v0
	v_mov_b32_e32 v75, v0
	v_mov_b32_e32 v80, v0
	v_mov_b32_e32 v81, v0
	v_mov_b32_e32 v82, v0
	v_mov_b32_e32 v83, v0
	v_mov_b32_e32 v88, v0
	v_mov_b32_e32 v89, v0
	v_mov_b32_e32 v90, v0
	v_mov_b32_e32 v91, v0
	v_mov_b32_e32 v98, v0
	v_mov_b32_e32 v99, v0
	v_mov_b32_e32 v100, v0
	v_mov_b32_e32 v101, v0
	v_mov_b32_e32 v106, v0
	v_mov_b32_e32 v107, v0
	v_mov_b32_e32 v108, v0
	v_mov_b32_e32 v109, v0
	v_mov_b32_e32 v114, v0
	v_mov_b32_e32 v115, v0
	v_mov_b32_e32 v116, v0
	v_mov_b32_e32 v117, v0
	v_mov_b32_e32 v126, v0
	v_mov_b32_e32 v127, v0
	v_mov_b32_e32 v128, v0
	v_mov_b32_e32 v129, v0
	v_mov_b32_e32 v68, v0
	v_mov_b32_e32 v69, v0
	v_mov_b32_e32 v70, v0
	v_mov_b32_e32 v71, v0
	v_mov_b32_e32 v76, v0
	v_mov_b32_e32 v77, v0
	v_mov_b32_e32 v78, v0
	v_mov_b32_e32 v79, v0
	v_mov_b32_e32 v84, v0
	v_mov_b32_e32 v85, v0
	v_mov_b32_e32 v86, v0
	v_mov_b32_e32 v87, v0
	v_mov_b32_e32 v94, v0
	v_mov_b32_e32 v95, v0
	v_mov_b32_e32 v96, v0
	v_mov_b32_e32 v97, v0
	v_mov_b32_e32 v102, v0
	v_mov_b32_e32 v103, v0
	v_mov_b32_e32 v104, v0
	v_mov_b32_e32 v105, v0
	v_mov_b32_e32 v110, v0
	v_mov_b32_e32 v111, v0
	v_mov_b32_e32 v112, v0
	v_mov_b32_e32 v113, v0
	v_mov_b32_e32 v118, v0
	v_mov_b32_e32 v119, v0
	v_mov_b32_e32 v120, v0
	v_mov_b32_e32 v121, v0
	v_mov_b32_e32 v122, v0
	v_mov_b32_e32 v123, v0
	v_mov_b32_e32 v124, v0
	v_mov_b32_e32 v125, v0
	s_cmp_lg_u32 s98, 0
	s_cbranch_scc1 .Lhalf511

.LBB0_514:
	v_lshl_or_b32 v146, s58, 7, v142
	v_lshl_add_u32 v144, s59, 8, v140
	v_ashrrev_i32_e32 v147, 31, v146
	s_movk_i32 s30, 0x1600
	s_and_b64 vcc, exec, s[4:5]
	v_mov_b32_e32 v160, 0xbfb8aa3b
	v_mov_b32_e32 v161, 0xbfb8aa3b
	v_mov_b64_e32 v[164:165], s[20:21]
	v_lshlrev_b64 v[166:167], 1, v[146:147]
	s_cmp_eq_u32 s98, 2
	s_cbranch_scc1 .Lswi_g4
	v_pk_mul_f32 v[150:151], v[122:123], v[160:161]
	v_pk_mul_f32 v[152:153], v[124:125], v[160:161]
	v_pk_mul_f32 v[154:155], v[118:119], v[160:161]
	v_pk_mul_f32 v[156:157], v[120:121], v[160:161]
	v_exp_f32_e32 v150, v150
	v_exp_f32_e32 v151, v151
	v_exp_f32_e32 v152, v152
	v_exp_f32_e32 v153, v153
	v_exp_f32_e32 v154, v154
	v_exp_f32_e32 v155, v155
	v_exp_f32_e32 v156, v156
	v_exp_f32_e32 v157, v157
	v_pk_add_f32 v[150:151], v[150:151], 1.0 op_sel_hi:[1,0]
	v_pk_add_f32 v[152:153], v[152:153], 1.0 op_sel_hi:[1,0]
	v_pk_add_f32 v[154:155], v[154:155], 1.0 op_sel_hi:[1,0]
	v_pk_add_f32 v[156:157], v[156:157], 1.0 op_sel_hi:[1,0]
	v_rcp_f32_e32 v150, v150
	v_rcp_f32_e32 v151, v151
	v_rcp_f32_e32 v152, v152
	v_rcp_f32_e32 v153, v153
	v_rcp_f32_e32 v154, v154
	v_rcp_f32_e32 v155, v155
	v_rcp_f32_e32 v156, v156
	v_rcp_f32_e32 v157, v157
	v_pk_mul_f32 v[122:123], v[122:123], v[150:151]
	v_pk_mul_f32 v[124:125], v[124:125], v[152:153]
	v_pk_mul_f32 v[118:119], v[118:119], v[154:155]
	v_pk_mul_f32 v[120:121], v[120:121], v[156:157]
	v_pk_mul_f32 v[122:123], v[126:127], v[122:123]
	v_pk_mul_f32 v[124:125], v[128:129], v[124:125]
	v_pk_mul_f32 v[118:119], v[114:115], v[118:119]
	v_pk_mul_f32 v[120:121], v[116:117], v[120:121]
	v_mov_b32_e32 v148, v144
	v_mad_i64_i32 v[162:163], s[28:29], v148, s30, v[164:165]
	v_cvt_pk_bf16_f32 v122, v122, v123
	v_cvt_pk_bf16_f32 v123, v124, v125
	v_cvt_pk_bf16_f32 v124, v118, v119
	v_cvt_pk_bf16_f32 v125, v120, v121
	v_lshl_add_u64 v[162:163], v[162:163], 0, v[166:167]
	global_store_dwordx4 v[162:163], v[122:125], off
	v_pk_mul_f32 v[150:151], v[110:111], v[160:161]
	v_pk_mul_f32 v[152:153], v[112:113], v[160:161]
	v_pk_mul_f32 v[154:155], v[102:103], v[160:161]
	v_pk_mul_f32 v[156:157], v[104:105], v[160:161]
	v_exp_f32_e32 v150, v150
	v_exp_f32_e32 v151, v151
	v_exp_f32_e32 v152, v152
	v_exp_f32_e32 v153, v153
	v_exp_f32_e32 v154, v154
	v_exp_f32_e32 v155, v155
	v_exp_f32_e32 v156, v156
	v_exp_f32_e32 v157, v157
	v_pk_add_f32 v[150:151], v[150:151], 1.0 op_sel_hi:[1,0]
	v_pk_add_f32 v[152:153], v[152:153], 1.0 op_sel_hi:[1,0]
	v_pk_add_f32 v[154:155], v[154:155], 1.0 op_sel_hi:[1,0]
	v_pk_add_f32 v[156:157], v[156:157], 1.0 op_sel_hi:[1,0]
	v_rcp_f32_e32 v150, v150
	v_rcp_f32_e32 v151, v151
	v_rcp_f32_e32 v152, v152
	v_rcp_f32_e32 v153, v153
	v_rcp_f32_e32 v154, v154
	v_rcp_f32_e32 v155, v155
	v_rcp_f32_e32 v156, v156
	v_rcp_f32_e32 v157, v157
	v_pk_mul_f32 v[110:111], v[110:111], v[150:151]
	v_pk_mul_f32 v[112:113], v[112:113], v[152:153]
	v_pk_mul_f32 v[102:103], v[102:103], v[154:155]
	v_pk_mul_f32 v[104:105], v[104:105], v[156:157]
	v_pk_mul_f32 v[110:111], v[106:107], v[110:111]
	v_pk_mul_f32 v[112:113], v[108:109], v[112:113]
	v_pk_mul_f32 v[102:103], v[98:99], v[102:103]
	v_pk_mul_f32 v[104:105], v[100:101], v[104:105]
	v_add_u32_e32 v148, 16, v144
	v_mad_i64_i32 v[162:163], s[28:29], v148, s30, v[164:165]
	v_cvt_pk_bf16_f32 v110, v110, v111
	v_cvt_pk_bf16_f32 v111, v112, v113
	v_cvt_pk_bf16_f32 v112, v102, v103
	v_cvt_pk_bf16_f32 v113, v104, v105
	v_lshl_add_u64 v[162:163], v[162:163], 0, v[166:167]
	global_store_dwordx4 v[162:163], v[110:113], off
	v_pk_mul_f32 v[150:151], v[94:95], v[160:161]
	v_pk_mul_f32 v[152:153], v[96:97], v[160:161]
	v_pk_mul_f32 v[154:155], v[84:85], v[160:161]
	v_pk_mul_f32 v[156:157], v[86:87], v[160:161]
	v_exp_f32_e32 v150, v150
	v_exp_f32_e32 v151, v151
	v_exp_f32_e32 v152, v152
	v_exp_f32_e32 v153, v153
	v_exp_f32_e32 v154, v154
	v_exp_f32_e32 v155, v155
	v_exp_f32_e32 v156, v156
	v_exp_f32_e32 v157, v157
	v_pk_add_f32 v[150:151], v[150:151], 1.0 op_sel_hi:[1,0]
	v_pk_add_f32 v[152:153], v[152:153], 1.0 op_sel_hi:[1,0]
	v_pk_add_f32 v[154:155], v[154:155], 1.0 op_sel_hi:[1,0]
	v_pk_add_f32 v[156:157], v[156:157], 1.0 op_sel_hi:[1,0]
	v_rcp_f32_e32 v150, v150
	v_rcp_f32_e32 v151, v151
	v_rcp_f32_e32 v152, v152
	v_rcp_f32_e32 v153, v153
	v_rcp_f32_e32 v154, v154
	v_rcp_f32_e32 v155, v155
	v_rcp_f32_e32 v156, v156
	v_rcp_f32_e32 v157, v157
	v_pk_mul_f32 v[94:95], v[94:95], v[150:151]
	v_pk_mul_f32 v[96:97], v[96:97], v[152:153]
	v_pk_mul_f32 v[84:85], v[84:85], v[154:155]
	v_pk_mul_f32 v[86:87], v[86:87], v[156:157]
	v_pk_mul_f32 v[94:95], v[88:89], v[94:95]
	v_pk_mul_f32 v[96:97], v[90:91], v[96:97]
	v_pk_mul_f32 v[84:85], v[80:81], v[84:85]
	v_pk_mul_f32 v[86:87], v[82:83], v[86:87]
	v_add_u32_e32 v148, 32, v144
	v_mad_i64_i32 v[162:163], s[28:29], v148, s30, v[164:165]
	v_cvt_pk_bf16_f32 v94, v94, v95
	v_cvt_pk_bf16_f32 v95, v96, v97
	v_cvt_pk_bf16_f32 v96, v84, v85
	v_cvt_pk_bf16_f32 v97, v86, v87
	v_lshl_add_u64 v[162:163], v[162:163], 0, v[166:167]
	global_store_dwordx4 v[162:163], v[94:97], off
	v_pk_mul_f32 v[150:151], v[76:77], v[160:161]
	v_pk_mul_f32 v[152:153], v[78:79], v[160:161]
	v_pk_mul_f32 v[154:155], v[68:69], v[160:161]
	v_pk_mul_f32 v[156:157], v[70:71], v[160:161]
	v_exp_f32_e32 v150, v150
	v_exp_f32_e32 v151, v151
	v_exp_f32_e32 v152, v152
	v_exp_f32_e32 v153, v153
	v_exp_f32_e32 v154, v154
	v_exp_f32_e32 v155, v155
	v_exp_f32_e32 v156, v156
	v_exp_f32_e32 v157, v157
	v_pk_add_f32 v[150:151], v[150:151], 1.0 op_sel_hi:[1,0]
	v_pk_add_f32 v[152:153], v[152:153], 1.0 op_sel_hi:[1,0]
	v_pk_add_f32 v[154:155], v[154:155], 1.0 op_sel_hi:[1,0]
	v_pk_add_f32 v[156:157], v[156:157], 1.0 op_sel_hi:[1,0]
	v_rcp_f32_e32 v150, v150
	v_rcp_f32_e32 v151, v151
	v_rcp_f32_e32 v152, v152
	v_rcp_f32_e32 v153, v153
	v_rcp_f32_e32 v154, v154
	v_rcp_f32_e32 v155, v155
	v_rcp_f32_e32 v156, v156
	v_rcp_f32_e32 v157, v157
	v_pk_mul_f32 v[76:77], v[76:77], v[150:151]
	v_pk_mul_f32 v[78:79], v[78:79], v[152:153]
	v_pk_mul_f32 v[68:69], v[68:69], v[154:155]
	v_pk_mul_f32 v[70:71], v[70:71], v[156:157]
	v_pk_mul_f32 v[76:77], v[72:73], v[76:77]
	v_pk_mul_f32 v[78:79], v[74:75], v[78:79]
	v_pk_mul_f32 v[68:69], v[64:65], v[68:69]
	v_pk_mul_f32 v[70:71], v[66:67], v[70:71]
	v_add_u32_e32 v148, 48, v144
	v_mad_i64_i32 v[162:163], s[28:29], v148, s30, v[164:165]
	v_cvt_pk_bf16_f32 v76, v76, v77
	v_cvt_pk_bf16_f32 v77, v78, v79
	v_cvt_pk_bf16_f32 v78, v68, v69
	v_cvt_pk_bf16_f32 v79, v70, v71
	v_lshl_add_u64 v[162:163], v[162:163], 0, v[166:167]
	global_store_dwordx4 v[162:163], v[76:79], off
	s_cmp_eq_u32 s98, 1
	s_cbranch_scc1 .Lswi_end
.Lswi_g4:
	v_pk_mul_f32 v[150:151], v[60:61], v[160:161]
	v_pk_mul_f32 v[152:153], v[62:63], v[160:161]
	v_pk_mul_f32 v[154:155], v[52:53], v[160:161]
	v_pk_mul_f32 v[156:157], v[54:55], v[160:161]
	v_exp_f32_e32 v150, v150
	v_exp_f32_e32 v151, v151
	v_exp_f32_e32 v152, v152
	v_exp_f32_e32 v153, v153
	v_exp_f32_e32 v154, v154
	v_exp_f32_e32 v155, v155
	v_exp_f32_e32 v156, v156
	v_exp_f32_e32 v157, v157
	v_pk_add_f32 v[150:151], v[150:151], 1.0 op_sel_hi:[1,0]
	v_pk_add_f32 v[152:153], v[152:153], 1.0 op_sel_hi:[1,0]
	v_pk_add_f32 v[154:155], v[154:155], 1.0 op_sel_hi:[1,0]
	v_pk_add_f32 v[156:157], v[156:157], 1.0 op_sel_hi:[1,0]
	v_rcp_f32_e32 v150, v150
	v_rcp_f32_e32 v151, v151
	v_rcp_f32_e32 v152, v152
	v_rcp_f32_e32 v153, v153
	v_rcp_f32_e32 v154, v154
	v_rcp_f32_e32 v155, v155
	v_rcp_f32_e32 v156, v156
	v_rcp_f32_e32 v157, v157
	v_pk_mul_f32 v[60:61], v[60:61], v[150:151]
	v_pk_mul_f32 v[62:63], v[62:63], v[152:153]
	v_pk_mul_f32 v[52:53], v[52:53], v[154:155]
	v_pk_mul_f32 v[54:55], v[54:55], v[156:157]
	v_pk_mul_f32 v[60:61], v[56:57], v[60:61]
	v_pk_mul_f32 v[62:63], v[58:59], v[62:63]
	v_pk_mul_f32 v[52:53], v[48:49], v[52:53]
	v_pk_mul_f32 v[54:55], v[50:51], v[54:55]
	v_add_u32_e32 v148, 128, v144
	v_mad_i64_i32 v[162:163], s[28:29], v148, s30, v[164:165]
	v_cvt_pk_bf16_f32 v60, v60, v61
	v_cvt_pk_bf16_f32 v61, v62, v63
	v_cvt_pk_bf16_f32 v62, v52, v53
	v_cvt_pk_bf16_f32 v63, v54, v55
	v_lshl_add_u64 v[162:163], v[162:163], 0, v[166:167]
	global_store_dwordx4 v[162:163], v[60:63], off
	v_pk_mul_f32 v[150:151], v[44:45], v[160:161]
	v_pk_mul_f32 v[152:153], v[46:47], v[160:161]
	v_pk_mul_f32 v[154:155], v[36:37], v[160:161]
	v_pk_mul_f32 v[156:157], v[38:39], v[160:161]
	v_exp_f32_e32 v150, v150
	v_exp_f32_e32 v151, v151
	v_exp_f32_e32 v152, v152
	v_exp_f32_e32 v153, v153
	v_exp_f32_e32 v154, v154
	v_exp_f32_e32 v155, v155
	v_exp_f32_e32 v156, v156
	v_exp_f32_e32 v157, v157
	v_pk_add_f32 v[150:151], v[150:151], 1.0 op_sel_hi:[1,0]
	v_pk_add_f32 v[152:153], v[152:153], 1.0 op_sel_hi:[1,0]
	v_pk_add_f32 v[154:155], v[154:155], 1.0 op_sel_hi:[1,0]
	v_pk_add_f32 v[156:157], v[156:157], 1.0 op_sel_hi:[1,0]
	v_rcp_f32_e32 v150, v150
	v_rcp_f32_e32 v151, v151
	v_rcp_f32_e32 v152, v152
	v_rcp_f32_e32 v153, v153
	v_rcp_f32_e32 v154, v154
	v_rcp_f32_e32 v155, v155
	v_rcp_f32_e32 v156, v156
	v_rcp_f32_e32 v157, v157
	v_pk_mul_f32 v[44:45], v[44:45], v[150:151]
	v_pk_mul_f32 v[46:47], v[46:47], v[152:153]
	v_pk_mul_f32 v[36:37], v[36:37], v[154:155]
	v_pk_mul_f32 v[38:39], v[38:39], v[156:157]
	v_pk_mul_f32 v[44:45], v[40:41], v[44:45]
	v_pk_mul_f32 v[46:47], v[42:43], v[46:47]
	v_pk_mul_f32 v[36:37], v[32:33], v[36:37]
	v_pk_mul_f32 v[38:39], v[34:35], v[38:39]
	v_add_u32_e32 v148, 144, v144
	v_mad_i64_i32 v[162:163], s[28:29], v148, s30, v[164:165]
	v_cvt_pk_bf16_f32 v44, v44, v45
	v_cvt_pk_bf16_f32 v45, v46, v47
	v_cvt_pk_bf16_f32 v46, v36, v37
	v_cvt_pk_bf16_f32 v47, v38, v39
	v_lshl_add_u64 v[162:163], v[162:163], 0, v[166:167]
	global_store_dwordx4 v[162:163], v[44:47], off
	v_pk_mul_f32 v[150:151], v[28:29], v[160:161]
	v_pk_mul_f32 v[152:153], v[30:31], v[160:161]
	v_pk_mul_f32 v[154:155], v[20:21], v[160:161]
	v_pk_mul_f32 v[156:157], v[22:23], v[160:161]
	v_exp_f32_e32 v150, v150
	v_exp_f32_e32 v151, v151
	v_exp_f32_e32 v152, v152
	v_exp_f32_e32 v153, v153
	v_exp_f32_e32 v154, v154
	v_exp_f32_e32 v155, v155
	v_exp_f32_e32 v156, v156
	v_exp_f32_e32 v157, v157
	v_pk_add_f32 v[150:151], v[150:151], 1.0 op_sel_hi:[1,0]
	v_pk_add_f32 v[152:153], v[152:153], 1.0 op_sel_hi:[1,0]
	v_pk_add_f32 v[154:155], v[154:155], 1.0 op_sel_hi:[1,0]
	v_pk_add_f32 v[156:157], v[156:157], 1.0 op_sel_hi:[1,0]
	v_rcp_f32_e32 v150, v150
	v_rcp_f32_e32 v151, v151
	v_rcp_f32_e32 v152, v152
	v_rcp_f32_e32 v153, v153
	v_rcp_f32_e32 v154, v154
	v_rcp_f32_e32 v155, v155
	v_rcp_f32_e32 v156, v156
	v_rcp_f32_e32 v157, v157
	v_pk_mul_f32 v[28:29], v[28:29], v[150:151]
	v_pk_mul_f32 v[30:31], v[30:31], v[152:153]
	v_pk_mul_f32 v[20:21], v[20:21], v[154:155]
	v_pk_mul_f32 v[22:23], v[22:23], v[156:157]
	v_pk_mul_f32 v[28:29], v[24:25], v[28:29]
	v_pk_mul_f32 v[30:31], v[26:27], v[30:31]
	v_pk_mul_f32 v[20:21], v[16:17], v[20:21]
	v_pk_mul_f32 v[22:23], v[18:19], v[22:23]
	v_add_u32_e32 v148, 160, v144
	v_mad_i64_i32 v[162:163], s[28:29], v148, s30, v[164:165]
	v_cvt_pk_bf16_f32 v28, v28, v29
	v_cvt_pk_bf16_f32 v29, v30, v31
	v_cvt_pk_bf16_f32 v30, v20, v21
	v_cvt_pk_bf16_f32 v31, v22, v23
	v_lshl_add_u64 v[162:163], v[162:163], 0, v[166:167]
	global_store_dwordx4 v[162:163], v[28:31], off
	v_pk_mul_f32 v[150:151], v[12:13], v[160:161]
	v_pk_mul_f32 v[152:153], v[14:15], v[160:161]
	v_pk_mul_f32 v[154:155], v[4:5], v[160:161]
	v_pk_mul_f32 v[156:157], v[6:7], v[160:161]
	v_exp_f32_e32 v150, v150
	v_exp_f32_e32 v151, v151
	v_exp_f32_e32 v152, v152
	v_exp_f32_e32 v153, v153
	v_exp_f32_e32 v154, v154
	v_exp_f32_e32 v155, v155
	v_exp_f32_e32 v156, v156
	v_exp_f32_e32 v157, v157
	v_pk_add_f32 v[150:151], v[150:151], 1.0 op_sel_hi:[1,0]
	v_pk_add_f32 v[152:153], v[152:153], 1.0 op_sel_hi:[1,0]
	v_pk_add_f32 v[154:155], v[154:155], 1.0 op_sel_hi:[1,0]
	v_pk_add_f32 v[156:157], v[156:157], 1.0 op_sel_hi:[1,0]
	v_rcp_f32_e32 v150, v150
	v_rcp_f32_e32 v151, v151
	v_rcp_f32_e32 v152, v152
	v_rcp_f32_e32 v153, v153
	v_rcp_f32_e32 v154, v154
	v_rcp_f32_e32 v155, v155
	v_rcp_f32_e32 v156, v156
	v_rcp_f32_e32 v157, v157
	v_pk_mul_f32 v[12:13], v[12:13], v[150:151]
	v_pk_mul_f32 v[14:15], v[14:15], v[152:153]
	v_pk_mul_f32 v[4:5], v[4:5], v[154:155]
	v_pk_mul_f32 v[6:7], v[6:7], v[156:157]
	v_pk_mul_f32 v[12:13], v[8:9], v[12:13]
	v_pk_mul_f32 v[14:15], v[10:11], v[14:15]
	v_pk_mul_f32 v[4:5], v[0:1], v[4:5]
	v_pk_mul_f32 v[6:7], v[2:3], v[6:7]
	v_add_u32_e32 v148, 176, v144
	v_mad_i64_i32 v[162:163], s[28:29], v148, s30, v[164:165]
	v_cvt_pk_bf16_f32 v12, v12, v13
	v_cvt_pk_bf16_f32 v13, v14, v15
	v_cvt_pk_bf16_f32 v14, v4, v5
	v_cvt_pk_bf16_f32 v15, v6, v7
	v_lshl_add_u64 v[162:163], v[162:163], 0, v[166:167]
	global_store_dwordx4 v[162:163], v[12:15], off
.Lswi_end:
	s_mov_b64 s[28:29], -1
	s_cbranch_vccnz .LBB0_498
	s_andn2_b64 vcc, exec, s[18:19]
	s_cbranch_vccnz .LBB0_497
	s_barrier
	s_branch .LBB0_497
.Lhalf511:
	s_add_i32 s62, s30, 2
	s_add_u32 s63, s28, 0x80
	s_addc_u32 s31, s29, 0
	s_add_i32 s66, 0, 0x10000
	s_cmp_eq_u32 s54, s30
	s_cselect_b32 s31, s7, s31
	s_cselect_b32 s30, s6, s63
	v_add_u32_e32 v156, s66, v141
	s_cselect_b32 s65, s27, s61
	s_cselect_b32 s64, s26, s60
	s_add_i32 s63, 0, 0x14000
	ds_read_b128 v[144:147], v156
	ds_read_b128 v[148:151], v156 offset:1024
	ds_read_b128 v[152:155], v156 offset:2048
	ds_read_b128 v[160:163], v156 offset:3072
	v_add_u32_e32 v156, s63, v141
	ds_read_b128 v[164:167], v156
	ds_read_b128 v[168:171], v156 offset:1024
	ds_read_b128 v[172:175], v156 offset:2048
	ds_read_b128 v[176:179], v156 offset:3072
	v_lshl_add_u64 v[156:157], s[28:29], 0, v[136:137]
	s_add_i32 m0, s47, 0xc000
	ds_read_b128 v[180:183], v143
	ds_read_b128 v[184:187], v143 offset:1024
	ds_read_b128 v[188:191], v143 offset:2048
	ds_read_b128 v[192:195], v143 offset:3072
	ds_read_b128 v[214:217], v143 offset:4096
	ds_read_b128 v[218:221], v143 offset:5120
	ds_read_b128 v[222:225], v143 offset:6144
	ds_read_b128 v[226:229], v143 offset:7168
	global_load_lds_dwordx4 v[156:157], off
	v_lshl_add_u64 v[156:157], s[28:29], 0, v[138:139]
	s_add_i32 m0, s47, 0xe000
	s_nop 0
	global_load_lds_dwordx4 v[156:157], off
	s_waitcnt vmcnt(8)
	s_waitcnt lgkmcnt(0)
	s_barrier
	s_setprio 1
	s_waitcnt lgkmcnt(0)
	s_cmp_eq_u32 s98, 2
	s_cbranch_scc1 .Lhskip1
	v_mfma_f32_16x16x32_bf16 v[122:125], v[144:147], v[180:183], v[122:125]
	v_mfma_f32_16x16x32_bf16 v[118:121], v[152:155], v[180:183], v[118:121]
	v_mfma_f32_16x16x32_bf16 v[110:113], v[144:147], v[188:191], v[110:113]
	v_mfma_f32_16x16x32_bf16 v[102:105], v[152:155], v[188:191], v[102:105]
	v_mfma_f32_16x16x32_bf16 v[94:97], v[144:147], v[214:217], v[94:97]
	v_mfma_f32_16x16x32_bf16 v[84:87], v[152:155], v[214:217], v[84:87]
	v_mfma_f32_16x16x32_bf16 v[76:79], v[144:147], v[222:225], v[76:79]
	v_mfma_f32_16x16x32_bf16 v[68:71], v[152:155], v[222:225], v[68:71]
	v_mfma_f32_16x16x32_bf16 v[122:125], v[148:151], v[184:187], v[122:125]
	v_mfma_f32_16x16x32_bf16 v[118:121], v[160:163], v[184:187], v[118:121]
	v_mfma_f32_16x16x32_bf16 v[110:113], v[148:151], v[192:195], v[110:113]
	v_mfma_f32_16x16x32_bf16 v[102:105], v[160:163], v[192:195], v[102:105]
	v_mfma_f32_16x16x32_bf16 v[94:97], v[148:151], v[218:221], v[94:97]
	v_mfma_f32_16x16x32_bf16 v[84:87], v[160:163], v[218:221], v[84:87]
	v_mfma_f32_16x16x32_bf16 v[76:79], v[148:151], v[226:229], v[76:79]
	v_mfma_f32_16x16x32_bf16 v[68:71], v[160:163], v[226:229], v[68:71]
	s_setprio 0
	s_setprio 1
	v_mfma_f32_16x16x32_bf16 v[126:129], v[164:167], v[180:183], v[126:129]
	v_mfma_f32_16x16x32_bf16 v[114:117], v[172:175], v[180:183], v[114:117]
	v_mfma_f32_16x16x32_bf16 v[106:109], v[164:167], v[188:191], v[106:109]
	v_mfma_f32_16x16x32_bf16 v[98:101], v[172:175], v[188:191], v[98:101]
	v_mfma_f32_16x16x32_bf16 v[88:91], v[164:167], v[214:217], v[88:91]
	v_mfma_f32_16x16x32_bf16 v[80:83], v[172:175], v[214:217], v[80:83]
	v_mfma_f32_16x16x32_bf16 v[72:75], v[164:167], v[222:225], v[72:75]
	v_mfma_f32_16x16x32_bf16 v[64:67], v[172:175], v[222:225], v[64:67]
	v_mfma_f32_16x16x32_bf16 v[126:129], v[168:171], v[184:187], v[126:129]
	v_mfma_f32_16x16x32_bf16 v[114:117], v[176:179], v[184:187], v[114:117]
	v_mfma_f32_16x16x32_bf16 v[106:109], v[168:171], v[192:195], v[106:109]
	v_mfma_f32_16x16x32_bf16 v[98:101], v[176:179], v[192:195], v[98:101]
	v_mfma_f32_16x16x32_bf16 v[88:91], v[168:171], v[218:221], v[88:91]
	v_mfma_f32_16x16x32_bf16 v[80:83], v[176:179], v[218:221], v[80:83]
	v_mfma_f32_16x16x32_bf16 v[72:75], v[168:171], v[226:229], v[72:75]
	v_mfma_f32_16x16x32_bf16 v[64:67], v[176:179], v[226:229], v[64:67]
.Lhskip1:
	s_setprio 0
	s_barrier
	s_add_i32 s66, s66, s44
	v_lshl_add_u64 v[156:157], s[64:65], 0, v[92:93]
	s_mov_b32 m0, s66
	ds_read_b128 v[180:183], v143 offset:16384
	ds_read_b128 v[184:187], v143 offset:17408
	ds_read_b128 v[188:191], v143 offset:18432
	ds_read_b128 v[192:195], v143 offset:19456
	ds_read_b128 v[214:217], v143 offset:20480
	ds_read_b128 v[218:221], v143 offset:21504
	ds_read_b128 v[222:225], v143 offset:22528
	ds_read_b128 v[226:229], v143 offset:23552
	global_load_lds_dwordx4 v[156:157], off
	s_add_i32 m0, s66, 0x2000
	v_lshl_add_u64 v[230:231], s[64:65], 0, v[134:135]
	s_add_u32 s64, s64, s10
	s_addc_u32 s65, s65, s11
	s_add_i32 s63, s63, s44
	global_load_lds_dwordx4 v[230:231], off
	v_lshl_add_u64 v[232:233], s[64:65], 0, v[92:93]
	s_mov_b32 m0, s63
	v_lshl_add_u64 v[234:235], s[64:65], 0, v[134:135]
	global_load_lds_dwordx4 v[232:233], off
	s_add_i32 m0, s63, 0x2000
	v_lshl_add_u64 v[236:237], s[30:31], 0, v[130:131]
	global_load_lds_dwordx4 v[234:235], off
	s_mov_b32 m0, s47
	v_lshl_add_u64 v[238:239], s[30:31], 0, v[132:133]
	global_load_lds_dwordx4 v[236:237], off
	s_mov_b32 m0, s48
	s_nop 0
	global_load_lds_dwordx4 v[238:239], off
	s_waitcnt vmcnt(8)
	s_waitcnt lgkmcnt(0)
	s_barrier
	s_setprio 1
	s_waitcnt lgkmcnt(0)
	s_cmp_eq_u32 s98, 1
	s_cbranch_scc1 .Lhskip3
	v_mfma_f32_16x16x32_bf16 v[60:63], v[144:147], v[180:183], v[60:63]
	v_mfma_f32_16x16x32_bf16 v[52:55], v[152:155], v[180:183], v[52:55]
	v_mfma_f32_16x16x32_bf16 v[44:47], v[144:147], v[188:191], v[44:47]
	v_mfma_f32_16x16x32_bf16 v[36:39], v[152:155], v[188:191], v[36:39]
	v_mfma_f32_16x16x32_bf16 v[28:31], v[144:147], v[214:217], v[28:31]
	v_mfma_f32_16x16x32_bf16 v[20:23], v[152:155], v[214:217], v[20:23]
	v_mfma_f32_16x16x32_bf16 v[12:15], v[144:147], v[222:225], v[12:15]
	v_mfma_f32_16x16x32_bf16 v[4:7], v[152:155], v[222:225], v[4:7]
	v_mfma_f32_16x16x32_bf16 v[60:63], v[148:151], v[184:187], v[60:63]
	v_mfma_f32_16x16x32_bf16 v[52:55], v[160:163], v[184:187], v[52:55]
	v_mfma_f32_16x16x32_bf16 v[44:47], v[148:151], v[192:195], v[44:47]
	v_mfma_f32_16x16x32_bf16 v[36:39], v[160:163], v[192:195], v[36:39]
	v_mfma_f32_16x16x32_bf16 v[28:31], v[148:151], v[218:221], v[28:31]
	v_mfma_f32_16x16x32_bf16 v[20:23], v[160:163], v[218:221], v[20:23]
	v_mfma_f32_16x16x32_bf16 v[12:15], v[148:151], v[226:229], v[12:15]
	v_mfma_f32_16x16x32_bf16 v[4:7], v[160:163], v[226:229], v[4:7]
	s_setprio 0
	s_setprio 1
	v_mfma_f32_16x16x32_bf16 v[56:59], v[164:167], v[180:183], v[56:59]
	v_mfma_f32_16x16x32_bf16 v[48:51], v[172:175], v[180:183], v[48:51]
	v_mfma_f32_16x16x32_bf16 v[40:43], v[164:167], v[188:191], v[40:43]
	v_mfma_f32_16x16x32_bf16 v[32:35], v[172:175], v[188:191], v[32:35]
	v_mfma_f32_16x16x32_bf16 v[24:27], v[164:167], v[214:217], v[24:27]
	v_mfma_f32_16x16x32_bf16 v[16:19], v[172:175], v[214:217], v[16:19]
	v_mfma_f32_16x16x32_bf16 v[8:11], v[164:167], v[222:225], v[8:11]
	v_mfma_f32_16x16x32_bf16 v[0:3], v[172:175], v[222:225], v[0:3]
	v_mfma_f32_16x16x32_bf16 v[56:59], v[168:171], v[184:187], v[56:59]
	v_mfma_f32_16x16x32_bf16 v[48:51], v[176:179], v[184:187], v[48:51]
	v_mfma_f32_16x16x32_bf16 v[40:43], v[168:171], v[192:195], v[40:43]
	v_mfma_f32_16x16x32_bf16 v[32:35], v[176:179], v[192:195], v[32:35]
	v_mfma_f32_16x16x32_bf16 v[24:27], v[168:171], v[218:221], v[24:27]
	v_mfma_f32_16x16x32_bf16 v[16:19], v[176:179], v[218:221], v[16:19]
	v_mfma_f32_16x16x32_bf16 v[8:11], v[168:171], v[226:229], v[8:11]
	v_mfma_f32_16x16x32_bf16 v[0:3], v[176:179], v[226:229], v[0:3]
.Lhskip3:
	s_setprio 0
	s_barrier
	s_add_i32 s63, 0, 0x18000
	v_add_u32_e32 v159, s63, v141
	s_add_i32 s64, 0, 0x1c000
	ds_read_b128 v[144:147], v159
	ds_read_b128 v[148:151], v159 offset:1024
	ds_read_b128 v[152:155], v159 offset:2048
	ds_read_b128 v[160:163], v159 offset:3072
	v_add_u32_e32 v159, s64, v141
	ds_read_b128 v[164:167], v159
	ds_read_b128 v[168:171], v159 offset:1024
	ds_read_b128 v[172:175], v159 offset:2048
	ds_read_b128 v[176:179], v159 offset:3072
	s_add_u32 s30, s30, s14
	s_addc_u32 s31, s31, s15
	s_mov_b32 m0, s49
	v_lshl_add_u64 v[240:241], s[30:31], 0, v[130:131]
	ds_read_b128 v[180:183], v143 offset:32768
	ds_read_b128 v[184:187], v143 offset:33792
	ds_read_b128 v[188:191], v143 offset:34816
	ds_read_b128 v[192:195], v143 offset:35840
	ds_read_b128 v[214:217], v143 offset:36864
	ds_read_b128 v[218:221], v143 offset:37888
	ds_read_b128 v[222:225], v143 offset:38912
	ds_read_b128 v[226:229], v143 offset:39936
	global_load_lds_dwordx4 v[240:241], off
	v_lshl_add_u64 v[240:241], s[30:31], 0, v[132:133]
	s_mov_b32 m0, s50
	s_nop 0
	global_load_lds_dwordx4 v[240:241], off
	s_waitcnt vmcnt(8)
	s_waitcnt lgkmcnt(0)
	s_barrier
	s_setprio 1
	s_waitcnt lgkmcnt(0)
	s_cmp_eq_u32 s98, 2
	s_cbranch_scc1 .Lhskip5
	v_mfma_f32_16x16x32_bf16 v[122:125], v[144:147], v[180:183], v[122:125]
	v_mfma_f32_16x16x32_bf16 v[118:121], v[152:155], v[180:183], v[118:121]
	v_mfma_f32_16x16x32_bf16 v[110:113], v[144:147], v[188:191], v[110:113]
	v_mfma_f32_16x16x32_bf16 v[102:105], v[152:155], v[188:191], v[102:105]
	v_mfma_f32_16x16x32_bf16 v[94:97], v[144:147], v[214:217], v[94:97]
	v_mfma_f32_16x16x32_bf16 v[84:87], v[152:155], v[214:217], v[84:87]
	v_mfma_f32_16x16x32_bf16 v[76:79], v[144:147], v[222:225], v[76:79]
	v_mfma_f32_16x16x32_bf16 v[68:71], v[152:155], v[222:225], v[68:71]
	v_mfma_f32_16x16x32_bf16 v[122:125], v[148:151], v[184:187], v[122:125]
	v_mfma_f32_16x16x32_bf16 v[118:121], v[160:163], v[184:187], v[118:121]
	v_mfma_f32_16x16x32_bf16 v[110:113], v[148:151], v[192:195], v[110:113]
	v_mfma_f32_16x16x32_bf16 v[102:105], v[160:163], v[192:195], v[102:105]
	v_mfma_f32_16x16x32_bf16 v[94:97], v[148:151], v[218:221], v[94:97]
	v_mfma_f32_16x16x32_bf16 v[84:87], v[160:163], v[218:221], v[84:87]
	v_mfma_f32_16x16x32_bf16 v[76:79], v[148:151], v[226:229], v[76:79]
	v_mfma_f32_16x16x32_bf16 v[68:71], v[160:163], v[226:229], v[68:71]
	s_setprio 0
	s_setprio 1
	v_mfma_f32_16x16x32_bf16 v[126:129], v[164:167], v[180:183], v[126:129]
	v_mfma_f32_16x16x32_bf16 v[114:117], v[172:175], v[180:183], v[114:117]
	v_mfma_f32_16x16x32_bf16 v[106:109], v[164:167], v[188:191], v[106:109]
	v_mfma_f32_16x16x32_bf16 v[98:101], v[172:175], v[188:191], v[98:101]
	v_mfma_f32_16x16x32_bf16 v[88:91], v[164:167], v[214:217], v[88:91]
	v_mfma_f32_16x16x32_bf16 v[80:83], v[172:175], v[214:217], v[80:83]
	v_mfma_f32_16x16x32_bf16 v[72:75], v[164:167], v[222:225], v[72:75]
	v_mfma_f32_16x16x32_bf16 v[64:67], v[172:175], v[222:225], v[64:67]
	v_mfma_f32_16x16x32_bf16 v[126:129], v[168:171], v[184:187], v[126:129]
	v_mfma_f32_16x16x32_bf16 v[114:117], v[176:179], v[184:187], v[114:117]
	v_mfma_f32_16x16x32_bf16 v[106:109], v[168:171], v[192:195], v[106:109]
	v_mfma_f32_16x16x32_bf16 v[98:101], v[176:179], v[192:195], v[98:101]
	v_mfma_f32_16x16x32_bf16 v[88:91], v[168:171], v[218:221], v[88:91]
	v_mfma_f32_16x16x32_bf16 v[80:83], v[176:179], v[218:221], v[80:83]
	v_mfma_f32_16x16x32_bf16 v[72:75], v[168:171], v[226:229], v[72:75]
	v_mfma_f32_16x16x32_bf16 v[64:67], v[176:179], v[226:229], v[64:67]
.Lhskip5:
	s_setprio 0
	s_barrier
	s_add_i32 s30, s63, s44
	v_lshl_add_u64 v[156:157], v[156:157], 0, s[80:81]
	s_mov_b32 m0, s30
	ds_read_b128 v[180:183], v143 offset:49152
	ds_read_b128 v[184:187], v143 offset:50176
	ds_read_b128 v[188:191], v143 offset:51200
	ds_read_b128 v[192:195], v143 offset:52224
	ds_read_b128 v[214:217], v143 offset:53248
	ds_read_b128 v[218:221], v143 offset:54272
	ds_read_b128 v[222:225], v143 offset:55296
	ds_read_b128 v[226:229], v143 offset:56320
	global_load_lds_dwordx4 v[156:157], off
	v_lshl_add_u64 v[156:157], v[230:231], 0, s[80:81]
	s_add_i32 m0, s30, 0x2000
	s_add_i32 s30, s64, s44
	global_load_lds_dwordx4 v[156:157], off
	v_lshl_add_u64 v[156:157], v[232:233], 0, s[80:81]
	s_mov_b32 m0, s30
	s_nop 0
	global_load_lds_dwordx4 v[156:157], off
	v_lshl_add_u64 v[156:157], v[234:235], 0, s[80:81]
	s_add_i32 m0, s30, 0x2000
	s_nop 0
	global_load_lds_dwordx4 v[156:157], off
	v_lshl_add_u64 v[156:157], v[236:237], 0, s[80:81]
	s_mov_b32 m0, s51
	s_nop 0
	global_load_lds_dwordx4 v[156:157], off
	v_lshl_add_u64 v[156:157], v[238:239], 0, s[80:81]
	s_mov_b32 m0, s52
	s_nop 0
	global_load_lds_dwordx4 v[156:157], off
	s_waitcnt vmcnt(8)
	s_waitcnt lgkmcnt(0)
	s_barrier
	s_setprio 1
	s_waitcnt lgkmcnt(0)
	s_cmp_eq_u32 s98, 1
	s_cbranch_scc1 .Lhskip7
	v_mfma_f32_16x16x32_bf16 v[60:63], v[144:147], v[180:183], v[60:63]
	v_mfma_f32_16x16x32_bf16 v[52:55], v[152:155], v[180:183], v[52:55]
	v_mfma_f32_16x16x32_bf16 v[44:47], v[144:147], v[188:191], v[44:47]
	v_mfma_f32_16x16x32_bf16 v[36:39], v[152:155], v[188:191], v[36:39]
	v_mfma_f32_16x16x32_bf16 v[28:31], v[144:147], v[214:217], v[28:31]
	v_mfma_f32_16x16x32_bf16 v[20:23], v[152:155], v[214:217], v[20:23]
	v_mfma_f32_16x16x32_bf16 v[12:15], v[144:147], v[222:225], v[12:15]
	v_mfma_f32_16x16x32_bf16 v[4:7], v[152:155], v[222:225], v[4:7]
	v_mfma_f32_16x16x32_bf16 v[60:63], v[148:151], v[184:187], v[60:63]
	v_mfma_f32_16x16x32_bf16 v[52:55], v[160:163], v[184:187], v[52:55]
	v_mfma_f32_16x16x32_bf16 v[44:47], v[148:151], v[192:195], v[44:47]
	v_mfma_f32_16x16x32_bf16 v[36:39], v[160:163], v[192:195], v[36:39]
	v_mfma_f32_16x16x32_bf16 v[28:31], v[148:151], v[218:221], v[28:31]
	v_mfma_f32_16x16x32_bf16 v[20:23], v[160:163], v[218:221], v[20:23]
	v_mfma_f32_16x16x32_bf16 v[12:15], v[148:151], v[226:229], v[12:15]
	v_mfma_f32_16x16x32_bf16 v[4:7], v[160:163], v[226:229], v[4:7]
	s_setprio 0
	s_setprio 1
	v_mfma_f32_16x16x32_bf16 v[56:59], v[164:167], v[180:183], v[56:59]
	v_mfma_f32_16x16x32_bf16 v[48:51], v[172:175], v[180:183], v[48:51]
	v_mfma_f32_16x16x32_bf16 v[40:43], v[164:167], v[188:191], v[40:43]
	v_mfma_f32_16x16x32_bf16 v[32:35], v[172:175], v[188:191], v[32:35]
	v_mfma_f32_16x16x32_bf16 v[24:27], v[164:167], v[214:217], v[24:27]
	v_mfma_f32_16x16x32_bf16 v[16:19], v[172:175], v[214:217], v[16:19]
	v_mfma_f32_16x16x32_bf16 v[8:11], v[164:167], v[222:225], v[8:11]
	v_mfma_f32_16x16x32_bf16 v[0:3], v[172:175], v[222:225], v[0:3]
	v_mfma_f32_16x16x32_bf16 v[56:59], v[168:171], v[184:187], v[56:59]
	v_mfma_f32_16x16x32_bf16 v[48:51], v[176:179], v[184:187], v[48:51]
	v_mfma_f32_16x16x32_bf16 v[40:43], v[168:171], v[192:195], v[40:43]
	v_mfma_f32_16x16x32_bf16 v[32:35], v[176:179], v[192:195], v[32:35]
	v_mfma_f32_16x16x32_bf16 v[24:27], v[168:171], v[218:221], v[24:27]
	v_mfma_f32_16x16x32_bf16 v[16:19], v[176:179], v[218:221], v[16:19]
	v_mfma_f32_16x16x32_bf16 v[8:11], v[168:171], v[226:229], v[8:11]
	v_mfma_f32_16x16x32_bf16 v[0:3], v[176:179], v[226:229], v[0:3]
.Lhskip7:
	s_setprio 0
	s_barrier
	s_add_u32 s28, s28, 0x100
	s_addc_u32 s29, s29, 0
	s_add_u32 s60, s60, 0x100
	s_addc_u32 s61, s61, 0
	s_cmp_ge_i32 s62, s53
	s_mov_b32 s30, s62
	s_cbranch_scc0 .Lhalf511
	s_branch .LBB0_512
